# MLP-up epilogue: redundant self-max before relu removed (hazard spacing kept with s_nop)
# baseline (speedup 1.0000x reference)
; __device__ __forceinline__ u32x4 pack8f(f32x4 v0, f32x4 v1) { u32x4 w; w.x = cvt_pk_bf16(v0[0], v0[1]); w.y = cvt_pk_bf16(v0[2], v0[3]); w.z = cvt_pk_bf16(v1[0], v1[1]); w.w = cvt_pk_bf16(v1[2], v1[3]); return w; }
;     __device__ __forceinline__ void operator()(const f32x4 (&acc)[2][2][4][2], const Unit& u, int wr, int wc, int fr, int fq) const {
;         const int row0 = u.pm * BM + wr * 64 + fr, c0 = u.pn * BM + wc * 32 + 8 * fq;
; #pragma unroll
;         for (int ai = 0; ai < 2; ++ai)
; #pragma unroll
;             for (int m = 0; m < 4; ++m) { bf16_t* rowp = O + (size_t)(row0 + ai * HALF + m * 16) * ldc + c0;
; #pragma unroll
;                 for (int bj = 0; bj < 2; ++bj) { f32x4 v0 = acc[ai][bj][m][0], v1 = acc[ai][bj][m][1];
; #pragma unroll
;                     for (int e = 0; e < 4; ++e) { const float a = fmaxf(v0[e], 0.f), b = fmaxf(v1[e], 0.f); v0[e] = a * a; v1[e] = b * b; }
;                     *(u32x4*)(rowp + bj * HALF) = pack8f(v0, v1); } }
;     }
.LBB0_778:
	v_lshl_add_u32 v152, s28, 8, v146
	v_lshl_or_b32 v144, s29, 8, v148
	v_ashrrev_i32_e32 v153, 31, v152
	v_ashrrev_i32_e32 v145, 31, v144
	v_lshlrev_b64 v[154:155], 14, v[152:153]
	v_lshl_add_u64 v[154:155], s[14:15], 0, v[154:155]
	v_lshlrev_b64 v[156:157], 1, v[144:145]
	v_max_f32_e32 v120, 0, v120
	v_max_f32_e32 v121, 0, v121
	v_lshl_add_u64 v[144:145], v[154:155], 0, v[156:157]
	v_pk_mul_f32 v[154:155], v[120:121], v[120:121]
	v_max_f32_e32 v122, 0, v122
	v_max_f32_e32 v124, 0, v124
	v_max_f32_e32 v125, 0, v125
	v_max_f32_e32 v120, 0, v126
	v_max_f32_e32 v121, 0, v127
	v_max_f32_e32 v123, 0, v123
	v_pk_mul_f32 v[124:125], v[124:125], v[124:125]
	v_pk_mul_f32 v[126:127], v[120:121], v[120:121]
	v_pk_mul_f32 v[158:159], v[122:123], v[122:123]
	v_cvt_pk_bf16_f32 v120, v124, v125
	v_cvt_pk_bf16_f32 v121, v126, v127
	v_cvt_pk_bf16_f32 v122, v154, v155
	v_cvt_pk_bf16_f32 v123, v158, v159
	v_max_f32_e32 v112, 0, v112
	v_max_f32_e32 v113, 0, v113
	global_store_dwordx4 v[144:145], v[120:123], off
	s_nop 1
	v_pk_mul_f32 v[120:121], v[112:113], v[112:113]
	v_max_f32_e32 v114, 0, v114
	v_max_f32_e32 v116, 0, v116
	v_max_f32_e32 v117, 0, v117
	v_max_f32_e32 v112, 0, v118
	v_max_f32_e32 v113, 0, v119
	v_max_f32_e32 v115, 0, v115
	v_pk_mul_f32 v[116:117], v[116:117], v[116:117]
	v_pk_mul_f32 v[118:119], v[112:113], v[112:113]
	v_pk_mul_f32 v[122:123], v[114:115], v[114:115]
	v_cvt_pk_bf16_f32 v112, v116, v117
	v_cvt_pk_bf16_f32 v113, v118, v119
	v_cvt_pk_bf16_f32 v114, v120, v121
	v_cvt_pk_bf16_f32 v115, v122, v123
	v_max_f32_e32 v104, 0, v104
	v_max_f32_e32 v105, 0, v105
	global_store_dwordx4 v[144:145], v[112:115], off offset:256
	s_nop 1
	v_or_b32_e32 v112, 16, v152
	v_pk_mul_f32 v[114:115], v[104:105], v[104:105]
	v_ashrrev_i32_e32 v113, 31, v112
	v_max_f32_e32 v106, 0, v106
	v_lshlrev_b64 v[112:113], 14, v[112:113]
	v_max_f32_e32 v108, 0, v108
	v_max_f32_e32 v109, 0, v109
	v_max_f32_e32 v104, 0, v110
	v_max_f32_e32 v105, 0, v111
	v_max_f32_e32 v107, 0, v107
	v_lshl_add_u64 v[112:113], s[14:15], 0, v[112:113]
	v_pk_mul_f32 v[108:109], v[108:109], v[108:109]
	v_pk_mul_f32 v[110:111], v[104:105], v[104:105]
	v_pk_mul_f32 v[116:117], v[106:107], v[106:107]
	v_lshl_add_u64 v[112:113], v[112:113], 0, v[156:157]
	v_cvt_pk_bf16_f32 v104, v108, v109
	v_cvt_pk_bf16_f32 v105, v110, v111
	v_cvt_pk_bf16_f32 v106, v114, v115
	v_cvt_pk_bf16_f32 v107, v116, v117
	v_max_f32_e32 v96, 0, v96
	v_max_f32_e32 v97, 0, v97
	global_store_dwordx4 v[112:113], v[104:107], off
	s_nop 1
	v_pk_mul_f32 v[104:105], v[96:97], v[96:97]
	v_max_f32_e32 v98, 0, v98
	v_max_f32_e32 v100, 0, v100
	v_max_f32_e32 v101, 0, v101
	v_max_f32_e32 v96, 0, v102
	v_max_f32_e32 v97, 0, v103
	v_max_f32_e32 v99, 0, v99
	v_pk_mul_f32 v[100:101], v[100:101], v[100:101]
	v_pk_mul_f32 v[102:103], v[96:97], v[96:97]
	v_pk_mul_f32 v[106:107], v[98:99], v[98:99]
	v_cvt_pk_bf16_f32 v96, v100, v101
	v_cvt_pk_bf16_f32 v97, v102, v103
	v_cvt_pk_bf16_f32 v98, v104, v105
	v_cvt_pk_bf16_f32 v99, v106, v107
	v_max_f32_e32 v88, 0, v88
	v_max_f32_e32 v89, 0, v89
	global_store_dwordx4 v[112:113], v[96:99], off offset:256
	s_nop 1
	v_or_b32_e32 v96, 32, v152
	v_pk_mul_f32 v[98:99], v[88:89], v[88:89]
	v_ashrrev_i32_e32 v97, 31, v96
	v_max_f32_e32 v90, 0, v90
	v_lshlrev_b64 v[96:97], 14, v[96:97]
	v_max_f32_e32 v92, 0, v92
	v_max_f32_e32 v93, 0, v93
	v_max_f32_e32 v88, 0, v94
	v_max_f32_e32 v89, 0, v95
	v_max_f32_e32 v91, 0, v91
	v_lshl_add_u64 v[96:97], s[14:15], 0, v[96:97]
	v_pk_mul_f32 v[92:93], v[92:93], v[92:93]
	v_pk_mul_f32 v[94:95], v[88:89], v[88:89]
	v_pk_mul_f32 v[100:101], v[90:91], v[90:91]
	v_lshl_add_u64 v[96:97], v[96:97], 0, v[156:157]
	v_cvt_pk_bf16_f32 v88, v92, v93
	v_cvt_pk_bf16_f32 v89, v94, v95
	v_cvt_pk_bf16_f32 v90, v98, v99
	v_cvt_pk_bf16_f32 v91, v100, v101
	v_max_f32_e32 v80, 0, v80
	v_max_f32_e32 v81, 0, v81
	global_store_dwordx4 v[96:97], v[88:91], off
	s_nop 1
	v_pk_mul_f32 v[88:89], v[80:81], v[80:81]
	v_max_f32_e32 v82, 0, v82
	v_max_f32_e32 v84, 0, v84
	v_max_f32_e32 v85, 0, v85
	v_max_f32_e32 v80, 0, v86
	v_max_f32_e32 v81, 0, v87
	v_max_f32_e32 v83, 0, v83
	v_pk_mul_f32 v[84:85], v[84:85], v[84:85]
	v_pk_mul_f32 v[86:87], v[80:81], v[80:81]
	v_pk_mul_f32 v[90:91], v[82:83], v[82:83]
	v_cvt_pk_bf16_f32 v80, v84, v85
	v_cvt_pk_bf16_f32 v81, v86, v87
	v_cvt_pk_bf16_f32 v82, v88, v89
	v_cvt_pk_bf16_f32 v83, v90, v91
	v_max_f32_e32 v72, 0, v72
	v_max_f32_e32 v73, 0, v73
	global_store_dwordx4 v[96:97], v[80:83], off offset:256
	s_nop 1
	v_or_b32_e32 v80, 48, v152
	v_pk_mul_f32 v[82:83], v[72:73], v[72:73]
	v_ashrrev_i32_e32 v81, 31, v80
	v_max_f32_e32 v74, 0, v74
	v_lshlrev_b64 v[80:81], 14, v[80:81]
	v_max_f32_e32 v76, 0, v76
	v_max_f32_e32 v77, 0, v77
	v_max_f32_e32 v72, 0, v78
	v_max_f32_e32 v73, 0, v79
	v_max_f32_e32 v75, 0, v75
	v_lshl_add_u64 v[80:81], s[14:15], 0, v[80:81]
	v_pk_mul_f32 v[76:77], v[76:77], v[76:77]
	v_pk_mul_f32 v[78:79], v[72:73], v[72:73]
	v_pk_mul_f32 v[84:85], v[74:75], v[74:75]
	v_lshl_add_u64 v[80:81], v[80:81], 0, v[156:157]
	v_cvt_pk_bf16_f32 v72, v76, v77
	v_cvt_pk_bf16_f32 v73, v78, v79
	v_cvt_pk_bf16_f32 v74, v82, v83
	v_cvt_pk_bf16_f32 v75, v84, v85
	v_max_f32_e32 v64, 0, v64
	v_max_f32_e32 v65, 0, v65
	global_store_dwordx4 v[80:81], v[72:75], off
	s_nop 1
	v_pk_mul_f32 v[72:73], v[64:65], v[64:65]
	v_max_f32_e32 v66, 0, v66
	v_max_f32_e32 v68, 0, v68
	v_max_f32_e32 v69, 0, v69
	v_max_f32_e32 v64, 0, v70
	v_max_f32_e32 v65, 0, v71
	v_max_f32_e32 v67, 0, v67
	v_pk_mul_f32 v[68:69], v[68:69], v[68:69]
	v_pk_mul_f32 v[70:71], v[64:65], v[64:65]
	v_pk_mul_f32 v[74:75], v[66:67], v[66:67]
	v_cvt_pk_bf16_f32 v64, v68, v69
; __device__ __forceinline__ u32x4 pack8f(f32x4 v0, f32x4 v1) { u32x4 w; w.x = cvt_pk_bf16(v0[0], v0[1]); w.y = cvt_pk_bf16(v0[2], v0[3]); w.z = cvt_pk_bf16(v1[0], v1[1]); w.w = cvt_pk_bf16(v1[2], v1[3]); return w; }
;     __device__ __forceinline__ void operator()(const f32x4 (&acc)[2][2][4][2], const Unit& u, int wr, int wc, int fr, int fq) const {
;         const int row0 = u.pm * BM + wr * 64 + fr, c0 = u.pn * BM + wc * 32 + 8 * fq;
; #pragma unroll
;         for (int ai = 0; ai < 2; ++ai)
; #pragma unroll
;             for (int m = 0; m < 4; ++m) { bf16_t* rowp = O + (size_t)(row0 + ai * HALF + m * 16) * ldc + c0;
; #pragma unroll
;                 for (int bj = 0; bj < 2; ++bj) { f32x4 v0 = acc[ai][bj][m][0], v1 = acc[ai][bj][m][1];
; #pragma unroll
;                     for (int e = 0; e < 4; ++e) { const float a = fmaxf(v0[e], 0.f), b = fmaxf(v1[e], 0.f); v0[e] = a * a; v1[e] = b * b; }
;                     *(u32x4*)(rowp + bj * HALF) = pack8f(v0, v1); } }
;     }
	v_cvt_pk_bf16_f32 v65, v70, v71
	v_cvt_pk_bf16_f32 v66, v72, v73
	v_cvt_pk_bf16_f32 v67, v74, v75
	v_max_f32_e32 v56, 0, v56
	v_max_f32_e32 v57, 0, v57
	global_store_dwordx4 v[80:81], v[64:67], off offset:256
	s_nop 1
	v_pk_mul_f32 v[66:67], v[56:57], v[56:57]
	v_max_f32_e32 v60, 0, v60
	v_max_f32_e32 v61, 0, v61
	v_max_f32_e32 v58, 0, v58
	v_pk_mul_f32 v[60:61], v[60:61], v[60:61]
	v_max_f32_e32 v56, 0, v62
	v_max_f32_e32 v57, 0, v63
	v_max_f32_e32 v59, 0, v59
	s_mov_b32 s21, 0x200000
	v_pk_mul_f32 v[62:63], v[56:57], v[56:57]
	v_pk_mul_f32 v[68:69], v[58:59], v[58:59]
	v_cvt_pk_bf16_f32 v56, v60, v61
	v_add_co_u32_e32 v60, vcc, s21, v144
	v_cvt_pk_bf16_f32 v57, v62, v63
	v_cvt_pk_bf16_f32 v58, v66, v67
	v_cvt_pk_bf16_f32 v59, v68, v69
	v_addc_co_u32_e32 v61, vcc, 0, v145, vcc
	v_max_f32_e32 v48, 0, v48
	v_max_f32_e32 v49, 0, v49
	global_store_dwordx4 v[60:61], v[56:59], off
	s_nop 1
	v_pk_mul_f32 v[56:57], v[48:49], v[48:49]
	v_max_f32_e32 v50, 0, v50
	v_max_f32_e32 v52, 0, v52
	v_max_f32_e32 v53, 0, v53
	v_max_f32_e32 v48, 0, v54
	v_max_f32_e32 v49, 0, v55
	v_max_f32_e32 v51, 0, v51
	s_mov_b64 s[28:29], 0x200000
	v_pk_mul_f32 v[52:53], v[52:53], v[52:53]
	v_pk_mul_f32 v[54:55], v[48:49], v[48:49]
	v_pk_mul_f32 v[58:59], v[50:51], v[50:51]
	v_lshl_add_u64 v[64:65], v[144:145], 0, s[28:29]
	v_cvt_pk_bf16_f32 v48, v52, v53
	v_cvt_pk_bf16_f32 v49, v54, v55
	v_cvt_pk_bf16_f32 v50, v56, v57
	v_cvt_pk_bf16_f32 v51, v58, v59
	v_max_f32_e32 v40, 0, v40
	v_max_f32_e32 v41, 0, v41
	global_store_dwordx4 v[64:65], v[48:51], off offset:256
	s_nop 1
	v_pk_mul_f32 v[50:51], v[40:41], v[40:41]
	v_max_f32_e32 v44, 0, v44
	v_max_f32_e32 v45, 0, v45
	v_max_f32_e32 v42, 0, v42
	v_pk_mul_f32 v[44:45], v[44:45], v[44:45]
	v_max_f32_e32 v40, 0, v46
	v_max_f32_e32 v41, 0, v47
	v_max_f32_e32 v43, 0, v43
	s_mov_b32 s21, 0x240000
	v_pk_mul_f32 v[46:47], v[40:41], v[40:41]
	v_pk_mul_f32 v[52:53], v[42:43], v[42:43]
	v_cvt_pk_bf16_f32 v40, v44, v45
	v_add_co_u32_e32 v44, vcc, s21, v144
	v_cvt_pk_bf16_f32 v41, v46, v47
	v_cvt_pk_bf16_f32 v42, v50, v51
	v_cvt_pk_bf16_f32 v43, v52, v53
	v_addc_co_u32_e32 v45, vcc, 0, v145, vcc
	v_max_f32_e32 v32, 0, v32
	v_max_f32_e32 v33, 0, v33
	global_store_dwordx4 v[44:45], v[40:43], off
	s_nop 1
	v_pk_mul_f32 v[40:41], v[32:33], v[32:33]
	v_max_f32_e32 v34, 0, v34
	v_max_f32_e32 v36, 0, v36
	v_max_f32_e32 v37, 0, v37
	v_max_f32_e32 v32, 0, v38
	v_max_f32_e32 v33, 0, v39
	v_max_f32_e32 v35, 0, v35
	s_mov_b64 s[28:29], 0x240000
	v_pk_mul_f32 v[36:37], v[36:37], v[36:37]
	v_pk_mul_f32 v[38:39], v[32:33], v[32:33]
	v_pk_mul_f32 v[42:43], v[34:35], v[34:35]
	v_lshl_add_u64 v[48:49], v[144:145], 0, s[28:29]
	v_cvt_pk_bf16_f32 v32, v36, v37
	v_cvt_pk_bf16_f32 v33, v38, v39
	v_cvt_pk_bf16_f32 v34, v40, v41
	v_cvt_pk_bf16_f32 v35, v42, v43
	v_max_f32_e32 v24, 0, v24
	v_max_f32_e32 v25, 0, v25
	global_store_dwordx4 v[48:49], v[32:35], off offset:256
	s_nop 1
	v_pk_mul_f32 v[34:35], v[24:25], v[24:25]
	v_max_f32_e32 v28, 0, v28
	v_max_f32_e32 v29, 0, v29
	v_max_f32_e32 v26, 0, v26
	v_pk_mul_f32 v[28:29], v[28:29], v[28:29]
	v_max_f32_e32 v24, 0, v30
	v_max_f32_e32 v25, 0, v31
	v_max_f32_e32 v27, 0, v27
	s_mov_b32 s21, 0x280000
	v_pk_mul_f32 v[30:31], v[24:25], v[24:25]
	v_pk_mul_f32 v[36:37], v[26:27], v[26:27]
	v_cvt_pk_bf16_f32 v24, v28, v29
	v_add_co_u32_e32 v28, vcc, s21, v144
	v_cvt_pk_bf16_f32 v25, v30, v31
	v_cvt_pk_bf16_f32 v26, v34, v35
	v_cvt_pk_bf16_f32 v27, v36, v37
	v_addc_co_u32_e32 v29, vcc, 0, v145, vcc
	v_max_f32_e32 v16, 0, v16
	v_max_f32_e32 v17, 0, v17
	global_store_dwordx4 v[28:29], v[24:27], off
	s_nop 1
	v_pk_mul_f32 v[24:25], v[16:17], v[16:17]
	v_max_f32_e32 v18, 0, v18
	v_max_f32_e32 v20, 0, v20
	v_max_f32_e32 v21, 0, v21
	v_max_f32_e32 v16, 0, v22
	v_max_f32_e32 v17, 0, v23
	v_max_f32_e32 v19, 0, v19
	s_mov_b64 s[28:29], 0x280000
	v_pk_mul_f32 v[20:21], v[20:21], v[20:21]
	v_pk_mul_f32 v[22:23], v[16:17], v[16:17]
	v_pk_mul_f32 v[26:27], v[18:19], v[18:19]
	v_lshl_add_u64 v[32:33], v[144:145], 0, s[28:29]
	v_cvt_pk_bf16_f32 v16, v20, v21
	v_cvt_pk_bf16_f32 v17, v22, v23
	v_cvt_pk_bf16_f32 v18, v24, v25
	v_cvt_pk_bf16_f32 v19, v26, v27
	v_max_f32_e32 v8, 0, v8
	v_max_f32_e32 v9, 0, v9
	global_store_dwordx4 v[32:33], v[16:19], off offset:256
	s_nop 1
	v_pk_mul_f32 v[18:19], v[8:9], v[8:9]
	v_max_f32_e32 v12, 0, v12
	v_max_f32_e32 v13, 0, v13
	v_max_f32_e32 v10, 0, v10
	v_pk_mul_f32 v[12:13], v[12:13], v[12:13]
	v_max_f32_e32 v8, 0, v14
	v_max_f32_e32 v9, 0, v15
	v_max_f32_e32 v11, 0, v11
	s_mov_b32 s21, 0x2c0000
	v_pk_mul_f32 v[14:15], v[8:9], v[8:9]
	v_pk_mul_f32 v[20:21], v[10:11], v[10:11]
	v_cvt_pk_bf16_f32 v8, v12, v13
	v_add_co_u32_e32 v12, vcc, s21, v144
	v_cvt_pk_bf16_f32 v9, v14, v15
	v_cvt_pk_bf16_f32 v10, v18, v19
	v_cvt_pk_bf16_f32 v11, v20, v21
	v_addc_co_u32_e32 v13, vcc, 0, v145, vcc
	v_max_f32_e32 v0, 0, v0
	v_max_f32_e32 v1, 0, v1
	global_store_dwordx4 v[12:13], v[8:11], off
	s_nop 1
	v_pk_mul_f32 v[8:9], v[0:1], v[0:1]
	v_max_f32_e32 v2, 0, v2
	v_max_f32_e32 v4, 0, v4
	v_max_f32_e32 v5, 0, v5
	v_max_f32_e32 v0, 0, v6
	v_max_f32_e32 v1, 0, v7
	v_max_f32_e32 v3, 0, v3
	s_mov_b64 s[28:29], 0x2c0000
	v_pk_mul_f32 v[4:5], v[4:5], v[4:5]
	v_pk_mul_f32 v[6:7], v[0:1], v[0:1]
	v_pk_mul_f32 v[10:11], v[2:3], v[2:3]
	v_lshl_add_u64 v[16:17], v[144:145], 0, s[28:29]
	v_cvt_pk_bf16_f32 v0, v4, v5
	v_cvt_pk_bf16_f32 v1, v6, v7
	v_cvt_pk_bf16_f32 v2, v8, v9
	v_cvt_pk_bf16_f32 v3, v10, v11
	s_andn2_b64 vcc, exec, s[38:39]
	s_mov_b64 s[28:29], -1
	global_store_dwordx4 v[16:17], v[0:3], off offset:256
	s_cbranch_vccnz .LBB0_767
	s_andn2_b64 vcc, exec, s[12:13]
	s_cbranch_vccnz .LBB0_766
	s_barrier
	s_branch .LBB0_766

; __device__ __forceinline__ unsigned xb_ld(unsigned* p)              { return __hip_atomic_load(p, __ATOMIC_RELAXED, __HIP_MEMORY_SCOPE_AGENT); }
; __device__ __forceinline__ unsigned xb_add(unsigned* p, unsigned v) { return __hip_atomic_fetch_add(p, v, __ATOMIC_RELAXED, __HIP_MEMORY_SCOPE_AGENT); }
; #define XB_SPIN(cond, bar) do { unsigned _sp = 0; while (cond) { __builtin_amdgcn_s_sleep(1); \
;     if ((++_sp & 255u) == 0u) { if (xb_ld(&(bar)[XB_TMO])) break; if (_sp > XB_SPIN_CAP) { atomicAdd(&(bar)[XB_TMO], 1u); break; } } } } while (0)
; __device__ __forceinline__ void xcd_barrier(const XcdBarrier& b) {
;     asm volatile("s_waitcnt vmcnt(0)" ::: "memory");
;     __syncthreads();
;     if (threadIdx.x == 0) {
;         unsigned* bar = b.bar;
;         __builtin_amdgcn_s_waitcnt(0);
;         unsigned nloc = b.st[0], nx = b.st[1];
;         if (nloc == 0u) { xcd_barrier_complete(bar, b.x, nloc, nx); b.st[0] = nloc; b.st[1] = nx; }
;         const unsigned old = xb_add(&bar[XB_XSUB(b.x)], 1u);
;         const unsigned gen = old / nloc;
;         if (old + 1u == (gen + 1u) * nloc) {
;             __builtin_amdgcn_fence(__ATOMIC_RELEASE, "agent");
;             asm volatile("s_waitcnt vmcnt(0)" ::: "memory");
;             const unsigned og = xb_add(&bar[XB_TOP], 1u);
;             const unsigned tg = og / nx;
;             if (og + 1u == (tg + 1u) * nx) xb_add(&bar[XB_TOPGEN], 1u);
;             else XB_SPIN(xb_ld(&bar[XB_TOPGEN]) == tg, bar);
;             __builtin_amdgcn_fence(__ATOMIC_ACQUIRE, "agent");
;             xb_add(&bar[XB_XGEN(b.x)], 1u);
;             asm volatile("s_waitcnt vmcnt(0)" ::: "memory");
;         } else {
;             XB_SPIN(xb_ld(&bar[XB_XGEN(b.x)]) == gen, bar);
;             __builtin_amdgcn_fence(__ATOMIC_ACQUIRE, "agent");
;             asm volatile("s_waitcnt vmcnt(0)" ::: "memory");
;         }
.LBB0_829:
	s_or_b64 exec, exec, s[4:5]
	s_nop 0
	s_and_saveexec_b64 s[4:5], s[6:7]
	s_cbranch_execz .LBB0_831
	v_mov_b32_e32 v2, 1
	global_atomic_add v[0:1], v2, off
